# hgrn_norm loop: all five loads issued together before the first wait (was two serialized load-wait stages per iteration)
# speedup vs baseline: 1.0131x; 1.0004x over previous
; DI unsigned pkh2(float a, float b) { typedef _Float16 h2 __attribute__((ext_vector_type(2))); h2 v; v[0] = (_Float16)a; v[1] = (_Float16)b; return __builtin_bit_cast(unsigned, v); }
; DI float bf2f(bf16_t v) { return __uint_as_float(((unsigned)v) << 16); }
; DI void hgrn_norm_phase(int wv, const P& p_, int slot) {
;     ...
;   for (size_t i = gtid; i < (size_t)MTOK * 1024 / 8; i += gsz) {
;     const size_t e = i * 8; const int row = (int)(e >> 10), col = (int)(e & 1023), hh = col >> 7, vv = col & 127;
;     const float rs = rsqrtf(sumsq[(size_t)row * 8 + hh] * (1.0f / 128.0f) + 1e-6f);
;     const bf16x8 o8 = *(const bf16x8*)(oraw + e), g8 = *(const bf16x8*)(hg + e);
;     u32x4 w;
; #pragma unroll
;     for (int j = 0; j < 4; ++j) w[j] = pkh2(bf2f((bf16_t)o8[2 * j]) * rs * gain[vv + 2 * j] * bf2f((bf16_t)g8[2 * j]), bf2f((bf16_t)o8[2 * j + 1]) * rs * gain[vv + 2 * j + 1] * bf2f((bf16_t)g8[2 * j + 1]));
;     *(u32x4*)(ob + e) = w;
;   }
.LBB0_525:
	v_lshrrev_b32_e32 v8, 2, v0
	v_and_b32_e32 v6, 0xfffe0, v8
	v_mov_b32_e32 v7, v32
	v_lshl_add_u64 v[6:7], s[8:9], 0, v[6:7]
	v_and_b32_e32 v8, 28, v8
	v_mov_b32_e32 v9, v32
	v_lshl_add_u64 v[6:7], v[6:7], 0, v[8:9]
	global_load_dword v26, v[6:7], off
	v_lshl_add_u64 v[24:25], s[6:7], 0, v[2:3]
	s_mov_b32 s12, 0x13000000
	v_and_b32_e32 v14, 0x78, v4
	v_lshlrev_b32_e32 v18, 2, v14
	v_lshl_add_u64 v[0:1], v[0:1], 0, s[14:15]
	v_lshl_add_u64 v[4:5], v[4:5], 0, s[18:19]
	v_lshl_add_u64 v[6:7], s[28:29], 0, v[2:3]
	global_load_dwordx4 v[6:9], v[6:7], off
	v_add_co_u32_e32 v10, vcc, s12, v24
	s_mov_b64 s[12:13], 0x3fffff
	s_nop 0
	v_addc_co_u32_e32 v11, vcc, 0, v25, vcc
	global_load_dwordx4 v[10:13], v[10:11], off
	v_lshl_add_u64 v[2:3], v[2:3], 0, s[16:17]
	global_load_dwordx4 v[14:17], v18, s[86:87] offset:16
	s_nop 0
	global_load_dwordx4 v[18:21], v18, s[86:87]
	s_waitcnt vmcnt(4)
	v_fmamk_f32 v26, v26, 0x3c000000, v232
	v_cmp_gt_f32_e32 vcc, s20, v26
	v_mul_f32_e32 v27, 0x4b800000, v26
	s_nop 0
	v_cndmask_b32_e32 v26, v26, v27, vcc
	v_rsq_f32_e32 v26, v26
	s_nop 0
	v_mul_f32_e32 v27, 0x45800000, v26
	v_cndmask_b32_e32 v22, v26, v27, vcc
	s_waitcnt vmcnt(0)
	v_and_b32_e32 v27, 0xffff0000, v6
	v_lshlrev_b32_e32 v26, 16, v6
	v_pk_mul_f32 v[26:27], v[22:23], v[26:27] op_sel_hi:[0,1]
	v_pk_mul_f32 v[18:19], v[18:19], v[26:27]
	v_and_b32_e32 v27, 0xffff0000, v10
	v_lshlrev_b32_e32 v26, 16, v10
	v_pk_mul_f32 v[18:19], v[18:19], v[26:27]
	s_nop 0
	v_cvt_pk_f16_f32 v6, v18, v19
	v_and_b32_e32 v19, 0xffff0000, v7
	v_lshlrev_b32_e32 v18, 16, v7
	v_pk_mul_f32 v[18:19], v[22:23], v[18:19] op_sel_hi:[0,1]
	v_pk_mul_f32 v[18:19], v[20:21], v[18:19]
	v_and_b32_e32 v21, 0xffff0000, v11
	v_lshlrev_b32_e32 v20, 16, v11
	v_pk_mul_f32 v[10:11], v[18:19], v[20:21]
	s_nop 0
	v_cvt_pk_f16_f32 v7, v10, v11
	v_and_b32_e32 v11, 0xffff0000, v8
	v_lshlrev_b32_e32 v10, 16, v8
	v_pk_mul_f32 v[10:11], v[22:23], v[10:11] op_sel_hi:[0,1]
	v_pk_mul_f32 v[10:11], v[14:15], v[10:11]
	v_and_b32_e32 v15, 0xffff0000, v12
	v_lshlrev_b32_e32 v14, 16, v12
	v_pk_mul_f32 v[10:11], v[10:11], v[14:15]
	v_and_b32_e32 v15, 0xffff0000, v13
	v_cvt_pk_f16_f32 v8, v10, v11
	v_and_b32_e32 v11, 0xffff0000, v9
	v_lshlrev_b32_e32 v10, 16, v9
	v_pk_mul_f32 v[10:11], v[22:23], v[10:11] op_sel_hi:[0,1]
	v_pk_mul_f32 v[10:11], v[10:11], v[16:17]
	v_lshlrev_b32_e32 v14, 16, v13
	v_pk_mul_f32 v[10:11], v[10:11], v[14:15]
	s_nop 0
	v_cvt_pk_f16_f32 v9, v10, v11
	v_add_co_u32_e32 v10, vcc, 0x1b000000, v24
	s_nop 1
	v_addc_co_u32_e32 v11, vcc, 0, v25, vcc
	v_cmp_lt_u64_e32 vcc, s[12:13], v[0:1]
	s_or_b64 s[10:11], vcc, s[10:11]
	global_store_dwordx4 v[10:11], v[6:9], off
	s_andn2_b64 exec, exec, s[10:11]
	s_cbranch_execnz .LBB0_525
